# attention branch folds: gate value + eight parked pieces loaded together, stores without drains (on top of v016)
# speedup vs baseline: 1.0144x; 1.0021x over previous
; __device__ __forceinline__ unsigned pk2(float lo, float hi) { const bfx2 b = __builtin_convertvector((f32x2){lo, hi}, bfx2); return __builtin_bit_cast(unsigned, b); }
; __device__ __forceinline__ float bflo(unsigned w) { return __uint_as_float(w << 16); }
; __device__ __forceinline__ float bfhi(unsigned w) { return __uint_as_float(w & 0xffff0000u); }
; #define PKP(var) unsigned char* var; { int l_ = threadIdx.x; asm volatile("" : "+v"(l_)); var = ws + WS_PARK + (size_t)(item8 + (l_ >> 6)) * 8192 + (l_ & 63) * 16; }
; __device__ __forceinline__ void attn_item(const P& p, Frame& F, const bool is_s, const int b, const int g, const int c) {
;     ...
;             if (ph == 3) { const float lt = l + __shfl_xor(l, 32); const float sc = lt > 0.f ? NGt[(size_t)mrow * 32 + 1 * 8 + h] / lt : 0.f;
;                 if (qvalid) { PKP(PK);
; #pragma unroll
;                     for (int dt = 0; dt < 4; ++dt)
; #pragma unroll
;                         for (int hf = 0; hf < 2; ++hf) { u32x4* yp = (u32x4*)(PK + (2 * dt + hf) * 1024); const u32x4 o = *yp; u32x4 w;
;                             w.x = pk2(bflo(o.x) + ot[dt][8 * hf + 0] * sc, bfhi(o.x) + ot[dt][8 * hf + 1] * sc); w.y = pk2(bflo(o.y) + ot[dt][8 * hf + 2] * sc, bfhi(o.y) + ot[dt][8 * hf + 3] * sc);
;                             w.z = pk2(bflo(o.z) + ot[dt][8 * hf + 4] * sc, bfhi(o.z) + ot[dt][8 * hf + 5] * sc); w.w = pk2(bflo(o.w) + ot[dt][8 * hf + 6] * sc, bfhi(o.w) + ot[dt][8 * hf + 7] * sc); *yp = w; } } }
.LBB0_2003:
	s_cmp_gt_u32 s5, 1
	s_cselect_b64 s[16:17], -1, 0
	s_cmp_lt_u32 s5, 2
	s_cselect_b64 s[18:19], -1, 0
	s_and_b64 vcc, exec, s[18:19]
	s_cbranch_vccnz .LBB0_2011
	s_cmp_lg_u32 s5, 3
	s_cbranch_scc1 .LBB0_2010
	v_mov_b32_e32 v8, 0
	s_and_saveexec_b64 s[0:1], s[22:23]
	v_mov_b32_e32 v1, v0
	v_readlane_b32 s2, v252, 13
	v_ashrrev_i32_e32 v2, 6, v1
	v_readlane_b32 s6, v254, 49
	v_add_u32_e32 v4, s2, v2
	v_ashrrev_i32_e32 v5, 31, v4
	v_lshlrev_b64 v[4:5], 13, v[4:5]
	v_readlane_b32 s7, v254, 50
	v_lshlrev_b32_e32 v1, 4, v1
	v_and_b32_e32 v2, 0x3f0, v1
	v_lshl_add_u64 v[4:5], s[6:7], 0, v[4:5]
	s_movk_i32 s2, 0x1000
	v_lshl_add_u64 v[4:5], v[4:5], 0, v[2:3]
	s_nop 0
	v_add_co_u32_e32 v10, vcc, s2, v4
	s_nop 1
	v_addc_co_u32_e32 v11, vcc, 0, v5, vcc
	global_load_dword v2, v[202:203], off offset:32
	global_load_dwordx4 v[114:117], v[4:5], off
	global_load_dwordx4 v[118:121], v[4:5], off offset:1024
	global_load_dwordx4 v[122:125], v[4:5], off offset:2048
	global_load_dwordx4 v[126:129], v[4:5], off offset:3072
	global_load_dwordx4 v[130:133], v[10:11], off
	global_load_dwordx4 v[134:137], v[10:11], off offset:1024
	global_load_dwordx4 v[138:141], v[10:11], off offset:2048
	global_load_dwordx4 v[142:145], v[10:11], off offset:3072
	s_or_b64 exec, exec, s[0:1]
	v_and_b32_e32 v7, 64, v221
	v_xor_b32_e32 v1, 32, v221
	v_add_u32_e32 v7, 64, v7
	v_cmp_lt_i32_e32 vcc, v1, v7
	s_nop 1
	v_cndmask_b32_e32 v1, v221, v1, vcc
	v_lshlrev_b32_e32 v1, 2, v1
	ds_bpermute_b32 v1, v1, v240
	s_waitcnt lgkmcnt(0)
	v_add_f32_e32 v1, v240, v1
	v_cmp_lt_f32_e32 vcc, 0, v1
	s_and_saveexec_b64 s[0:1], vcc
	s_waitcnt vmcnt(0)
	v_div_scale_f32 v12, s[6:7], v1, v1, v2
	v_rcp_f32_e32 v13, v12
	v_div_scale_f32 v14, vcc, v2, v1, v2
	v_fma_f32 v15, -v12, v13, 1.0
	v_fmac_f32_e32 v13, v15, v13
	v_mul_f32_e32 v15, v14, v13
	v_fma_f32 v8, -v12, v15, v14
	v_fmac_f32_e32 v15, v8, v13
	v_fma_f32 v12, -v12, v15, v14
	v_div_fmas_f32 v12, v12, v13, v15
	v_div_fixup_f32 v8, v12, v1, v2
	s_or_b64 exec, exec, s[0:1]
	s_and_saveexec_b64 s[0:1], s[22:23]
	s_cbranch_execz .LBB0_2009
; __device__ __forceinline__ unsigned pk2(float lo, float hi) { const bfx2 b = __builtin_convertvector((f32x2){lo, hi}, bfx2); return __builtin_bit_cast(unsigned, b); }
; __device__ __forceinline__ float bflo(unsigned w) { return __uint_as_float(w << 16); }
; __device__ __forceinline__ float bfhi(unsigned w) { return __uint_as_float(w & 0xffff0000u); }
; __device__ __forceinline__ void attn_item(const P& p, Frame& F, const bool is_s, const int b, const int g, const int c) {
;     ...
;                         for (int hf = 0; hf < 2; ++hf) { u32x4* yp = (u32x4*)(PK + (2 * dt + hf) * 1024); const u32x4 o = *yp; u32x4 w;
;                             w.x = pk2(bflo(o.x) + ot[dt][8 * hf + 0] * sc, bfhi(o.x) + ot[dt][8 * hf + 1] * sc); w.y = pk2(bflo(o.y) + ot[dt][8 * hf + 2] * sc, bfhi(o.y) + ot[dt][8 * hf + 3] * sc);
;                             w.z = pk2(bflo(o.z) + ot[dt][8 * hf + 4] * sc, bfhi(o.z) + ot[dt][8 * hf + 5] * sc); w.w = pk2(bflo(o.w) + ot[dt][8 * hf + 6] * sc, bfhi(o.w) + ot[dt][8 * hf + 7] * sc); *yp = w; } } }
	s_waitcnt vmcnt(0)
	v_lshlrev_b32_e32 v6, 16, v114
	v_and_b32_e32 v7, 0xffff0000, v114
	v_pk_fma_f32 v[6:7], v[66:67], v[8:9], v[6:7] op_sel_hi:[1,0,1]
	s_nop 0
	v_cvt_pk_bf16_f32 v114, v6, v7
	v_lshlrev_b32_e32 v12, 16, v115
	v_and_b32_e32 v13, 0xffff0000, v115
	v_pk_fma_f32 v[12:13], v[68:69], v[8:9], v[12:13] op_sel_hi:[1,0,1]
	s_nop 0
	v_cvt_pk_bf16_f32 v115, v12, v13
	v_lshlrev_b32_e32 v14, 16, v116
	v_and_b32_e32 v15, 0xffff0000, v116
	v_pk_fma_f32 v[14:15], v[70:71], v[8:9], v[14:15] op_sel_hi:[1,0,1]
	s_nop 0
	v_cvt_pk_bf16_f32 v116, v14, v15
	v_lshlrev_b32_e32 v16, 16, v117
	v_and_b32_e32 v17, 0xffff0000, v117
	v_pk_fma_f32 v[16:17], v[72:73], v[8:9], v[16:17] op_sel_hi:[1,0,1]
	s_nop 0
	v_cvt_pk_bf16_f32 v117, v16, v17
	global_store_dwordx4 v[4:5], v[114:117], off
	v_lshlrev_b32_e32 v6, 16, v118
	v_and_b32_e32 v7, 0xffff0000, v118
	v_pk_fma_f32 v[6:7], v[74:75], v[8:9], v[6:7] op_sel_hi:[1,0,1]
	s_nop 0
	v_cvt_pk_bf16_f32 v118, v6, v7
	v_lshlrev_b32_e32 v12, 16, v119
	v_and_b32_e32 v13, 0xffff0000, v119
	v_pk_fma_f32 v[12:13], v[76:77], v[8:9], v[12:13] op_sel_hi:[1,0,1]
	s_nop 0
	v_cvt_pk_bf16_f32 v119, v12, v13
	v_lshlrev_b32_e32 v14, 16, v120
	v_and_b32_e32 v15, 0xffff0000, v120
	v_pk_fma_f32 v[14:15], v[78:79], v[8:9], v[14:15] op_sel_hi:[1,0,1]
	s_nop 0
	v_cvt_pk_bf16_f32 v120, v14, v15
	v_lshlrev_b32_e32 v16, 16, v121
	v_and_b32_e32 v17, 0xffff0000, v121
	v_pk_fma_f32 v[16:17], v[80:81], v[8:9], v[16:17] op_sel_hi:[1,0,1]
	s_nop 0
	v_cvt_pk_bf16_f32 v121, v16, v17
	global_store_dwordx4 v[4:5], v[118:121], off offset:1024
	v_lshlrev_b32_e32 v6, 16, v122
	v_and_b32_e32 v7, 0xffff0000, v122
	v_pk_fma_f32 v[6:7], v[50:51], v[8:9], v[6:7] op_sel_hi:[1,0,1]
	s_nop 0
	v_cvt_pk_bf16_f32 v122, v6, v7
	v_lshlrev_b32_e32 v12, 16, v123
	v_and_b32_e32 v13, 0xffff0000, v123
	v_pk_fma_f32 v[12:13], v[52:53], v[8:9], v[12:13] op_sel_hi:[1,0,1]
	s_nop 0
	v_cvt_pk_bf16_f32 v123, v12, v13
	v_lshlrev_b32_e32 v14, 16, v124
	v_and_b32_e32 v15, 0xffff0000, v124
	v_pk_fma_f32 v[14:15], v[54:55], v[8:9], v[14:15] op_sel_hi:[1,0,1]
	s_nop 0
	v_cvt_pk_bf16_f32 v124, v14, v15
	v_lshlrev_b32_e32 v16, 16, v125
	v_and_b32_e32 v17, 0xffff0000, v125
	v_pk_fma_f32 v[16:17], v[56:57], v[8:9], v[16:17] op_sel_hi:[1,0,1]
	s_nop 0
	v_cvt_pk_bf16_f32 v125, v16, v17
	global_store_dwordx4 v[4:5], v[122:125], off offset:2048
	v_lshlrev_b32_e32 v6, 16, v126
	v_and_b32_e32 v7, 0xffff0000, v126
	v_pk_fma_f32 v[6:7], v[58:59], v[8:9], v[6:7] op_sel_hi:[1,0,1]
	s_nop 0
	v_cvt_pk_bf16_f32 v126, v6, v7
	v_lshlrev_b32_e32 v12, 16, v127
	v_and_b32_e32 v13, 0xffff0000, v127
	v_pk_fma_f32 v[12:13], v[60:61], v[8:9], v[12:13] op_sel_hi:[1,0,1]
	s_nop 0
	v_cvt_pk_bf16_f32 v127, v12, v13
	v_lshlrev_b32_e32 v14, 16, v128
	v_and_b32_e32 v15, 0xffff0000, v128
	v_pk_fma_f32 v[14:15], v[62:63], v[8:9], v[14:15] op_sel_hi:[1,0,1]
	s_nop 0
	v_cvt_pk_bf16_f32 v128, v14, v15
	v_lshlrev_b32_e32 v16, 16, v129
	v_and_b32_e32 v17, 0xffff0000, v129
	v_pk_fma_f32 v[16:17], v[64:65], v[8:9], v[16:17] op_sel_hi:[1,0,1]
	s_nop 0
	v_cvt_pk_bf16_f32 v129, v16, v17
	global_store_dwordx4 v[4:5], v[126:129], off offset:3072
	v_lshlrev_b32_e32 v6, 16, v130
	v_and_b32_e32 v7, 0xffff0000, v130
	v_pk_fma_f32 v[6:7], v[34:35], v[8:9], v[6:7] op_sel_hi:[1,0,1]
	s_nop 0
	v_cvt_pk_bf16_f32 v130, v6, v7
	v_lshlrev_b32_e32 v12, 16, v131
	v_and_b32_e32 v13, 0xffff0000, v131
	v_pk_fma_f32 v[12:13], v[36:37], v[8:9], v[12:13] op_sel_hi:[1,0,1]
	s_nop 0
	v_cvt_pk_bf16_f32 v131, v12, v13
	v_lshlrev_b32_e32 v14, 16, v132
	v_and_b32_e32 v15, 0xffff0000, v132
	v_pk_fma_f32 v[14:15], v[38:39], v[8:9], v[14:15] op_sel_hi:[1,0,1]
	s_nop 0
	v_cvt_pk_bf16_f32 v132, v14, v15
	v_lshlrev_b32_e32 v16, 16, v133
	v_and_b32_e32 v17, 0xffff0000, v133
	v_pk_fma_f32 v[16:17], v[40:41], v[8:9], v[16:17] op_sel_hi:[1,0,1]
	s_nop 0
	v_cvt_pk_bf16_f32 v133, v16, v17
	global_store_dwordx4 v[10:11], v[130:133], off
	v_lshlrev_b32_e32 v6, 16, v134
	v_and_b32_e32 v7, 0xffff0000, v134
	v_pk_fma_f32 v[6:7], v[42:43], v[8:9], v[6:7] op_sel_hi:[1,0,1]
	s_nop 0
	v_cvt_pk_bf16_f32 v134, v6, v7
	v_lshlrev_b32_e32 v12, 16, v135
	v_and_b32_e32 v13, 0xffff0000, v135
	v_pk_fma_f32 v[12:13], v[44:45], v[8:9], v[12:13] op_sel_hi:[1,0,1]
	s_nop 0
	v_cvt_pk_bf16_f32 v135, v12, v13
	v_lshlrev_b32_e32 v14, 16, v136
	v_and_b32_e32 v15, 0xffff0000, v136
	v_pk_fma_f32 v[14:15], v[46:47], v[8:9], v[14:15] op_sel_hi:[1,0,1]
	s_nop 0
	v_cvt_pk_bf16_f32 v136, v14, v15
	v_lshlrev_b32_e32 v16, 16, v137
	v_and_b32_e32 v17, 0xffff0000, v137
	v_pk_fma_f32 v[16:17], v[48:49], v[8:9], v[16:17] op_sel_hi:[1,0,1]
	s_nop 0
	v_cvt_pk_bf16_f32 v137, v16, v17
	global_store_dwordx4 v[10:11], v[134:137], off offset:1024
	v_lshlrev_b32_e32 v6, 16, v138
	v_and_b32_e32 v7, 0xffff0000, v138
	v_pk_fma_f32 v[6:7], v[18:19], v[8:9], v[6:7] op_sel_hi:[1,0,1]
	s_nop 0
	v_cvt_pk_bf16_f32 v138, v6, v7
	v_lshlrev_b32_e32 v12, 16, v139
	v_and_b32_e32 v13, 0xffff0000, v139
	v_pk_fma_f32 v[12:13], v[20:21], v[8:9], v[12:13] op_sel_hi:[1,0,1]
	s_nop 0
	v_cvt_pk_bf16_f32 v139, v12, v13
	v_lshlrev_b32_e32 v14, 16, v140
	v_and_b32_e32 v15, 0xffff0000, v140
	v_pk_fma_f32 v[14:15], v[22:23], v[8:9], v[14:15] op_sel_hi:[1,0,1]
	s_nop 0
	v_cvt_pk_bf16_f32 v140, v14, v15
	v_lshlrev_b32_e32 v16, 16, v141
	v_and_b32_e32 v17, 0xffff0000, v141
	v_pk_fma_f32 v[16:17], v[24:25], v[8:9], v[16:17] op_sel_hi:[1,0,1]
	s_nop 0
	v_cvt_pk_bf16_f32 v141, v16, v17
	global_store_dwordx4 v[10:11], v[138:141], off offset:2048
	v_lshlrev_b32_e32 v6, 16, v142
	v_and_b32_e32 v7, 0xffff0000, v142
	v_pk_fma_f32 v[6:7], v[26:27], v[8:9], v[6:7] op_sel_hi:[1,0,1]
	s_nop 0
	v_cvt_pk_bf16_f32 v142, v6, v7
	v_lshlrev_b32_e32 v12, 16, v143
	v_and_b32_e32 v13, 0xffff0000, v143
	v_pk_fma_f32 v[12:13], v[28:29], v[8:9], v[12:13] op_sel_hi:[1,0,1]
	s_nop 0
	v_cvt_pk_bf16_f32 v143, v12, v13
	v_lshlrev_b32_e32 v14, 16, v144
	v_and_b32_e32 v15, 0xffff0000, v144
	v_pk_fma_f32 v[14:15], v[30:31], v[8:9], v[14:15] op_sel_hi:[1,0,1]
	s_nop 0
	v_cvt_pk_bf16_f32 v144, v14, v15
	v_lshlrev_b32_e32 v16, 16, v145
	v_and_b32_e32 v17, 0xffff0000, v145
	v_pk_fma_f32 v[16:17], v[32:33], v[8:9], v[16:17] op_sel_hi:[1,0,1]
	s_nop 0
	v_cvt_pk_bf16_f32 v145, v16, v17
	global_store_dwordx4 v[10:11], v[142:145], off offset:3072

; __device__ __forceinline__ unsigned pk2(float lo, float hi) { const bfx2 b = __builtin_convertvector((f32x2){lo, hi}, bfx2); return __builtin_bit_cast(unsigned, b); }
; __device__ __forceinline__ float bflo(unsigned w) { return __uint_as_float(w << 16); }
; __device__ __forceinline__ float bfhi(unsigned w) { return __uint_as_float(w & 0xffff0000u); }
; #define PKP(var) unsigned char* var; { int l_ = threadIdx.x; asm volatile("" : "+v"(l_)); var = ws + WS_PARK + (size_t)(item8 + (l_ >> 6)) * 8192 + (l_ & 63) * 16; }
; __device__ __forceinline__ void attn_item(const P& p, Frame& F, const bool is_s, const int b, const int g, const int c) {
;     ...
;     { const float lt = l + __shfl_xor(l, 32); const float sc = lt > 0.f ? NGt[(size_t)mrow * 32 + 2 * 8 + h] / lt : 0.f;
;       if (qvalid) { PKP(PK);
; #pragma unroll
;           for (int dt = 0; dt < 4; ++dt)
; #pragma unroll
;               for (int hf = 0; hf < 2; ++hf) { const u32x4 o4 = *(const u32x4*)(PK + (2 * dt + hf) * 1024);
; #pragma unroll
;                   for (int rr = 0; rr < 2; ++rr) { const int r4 = 2 * hf + rr; const int d0 = 32 * dt + 8 * r4 + 4 * half; const u32x2 o = rr ? (u32x2){o4.z, o4.w} : (u32x2){o4.x, o4.y};
;                       u32x2 w; w.x = pk2(bflo(o.x) + ot[dt][4 * r4 + 0] * sc, bfhi(o.x) + ot[dt][4 * r4 + 1] * sc); w.y = pk2(bflo(o.y) + ot[dt][4 * r4 + 2] * sc, bfhi(o.y) + ot[dt][4 * r4 + 3] * sc);
;                       *(u32x2*)(YN + (size_t)mrow * 1024 + h * 128 + d0) = w; } } } }
.LBB0_2141:
	s_waitcnt vmcnt(0)
	s_and_saveexec_b64 s[0:1], s[22:23]
	v_mov_b32_e32 v1, v0
	v_readlane_b32 s2, v252, 13
	v_ashrrev_i32_e32 v2, 6, v1
	v_lshlrev_b32_e32 v1, 4, v1
	v_add_u32_e32 v6, s2, v2
	v_ashrrev_i32_e32 v7, 31, v6
	v_readlane_b32 s2, v254, 49
	v_lshlrev_b64 v[6:7], 13, v[6:7]
	v_readlane_b32 s3, v254, 50
	v_and_b32_e32 v2, 0x3f0, v1
	s_nop 0
	v_lshl_add_u64 v[6:7], s[2:3], 0, v[6:7]
	v_lshl_add_u64 v[8:9], v[6:7], 0, v[2:3]
	s_movk_i32 s2, 0x1000
	s_nop 0
	v_add_co_u32_e32 v10, vcc, s2, v8
	s_nop 1
	v_addc_co_u32_e32 v11, vcc, 0, v9, vcc
	global_load_dword v16, v[202:203], off offset:64
	global_load_dwordx4 v[114:117], v[8:9], off
	global_load_dwordx4 v[118:121], v[8:9], off offset:1024
	global_load_dwordx4 v[122:125], v[8:9], off offset:2048
	global_load_dwordx4 v[126:129], v[8:9], off offset:3072
	global_load_dwordx4 v[130:133], v[10:11], off
	global_load_dwordx4 v[134:137], v[10:11], off offset:1024
	global_load_dwordx4 v[138:141], v[10:11], off offset:2048
	global_load_dwordx4 v[142:145], v[10:11], off offset:3072
	v_readlane_b32 s2, v252, 23
	v_readlane_b32 s3, v252, 24
	v_lshlrev_b32_e32 v2, 1, v229
	s_nop 1
	v_lshl_add_u64 v[6:7], s[2:3], 0, v[200:201]
	v_readlane_b32 s2, v252, 45
	s_nop 1
	s_lshl_b32 s44, s2, 1
	s_nop 0
	v_lshl_add_u64 v[6:7], v[6:7], 0, s[44:45]
	v_lshl_add_u64 v[6:7], v[6:7], 0, v[2:3]
	s_or_b64 exec, exec, s[0:1]
	v_and_b32_e32 v13, 64, v221
	v_xor_b32_e32 v1, 32, v221
	v_add_u32_e32 v13, 64, v13
	v_cmp_lt_i32_e32 vcc, v1, v13
	v_mov_b32_e32 v4, 0
	s_nop 0
	v_cndmask_b32_e32 v1, v221, v1, vcc
	v_lshlrev_b32_e32 v1, 2, v1
	ds_bpermute_b32 v1, v1, v240
	s_waitcnt lgkmcnt(0)
	v_add_f32_e32 v1, v240, v1
	v_cmp_lt_f32_e32 vcc, 0, v1
	s_and_saveexec_b64 s[0:1], vcc
	s_waitcnt vmcnt(0)
	v_div_scale_f32 v4, s[2:3], v1, v1, v16
	v_rcp_f32_e32 v5, v4
	v_div_scale_f32 v12, vcc, v16, v1, v16
	v_fma_f32 v13, -v4, v5, 1.0
	v_fmac_f32_e32 v5, v13, v5
	v_mul_f32_e32 v13, v12, v5
	v_fma_f32 v14, -v4, v13, v12
	v_fmac_f32_e32 v13, v14, v5
	v_fma_f32 v4, -v4, v13, v12
	v_div_fmas_f32 v4, v4, v5, v13
	v_div_fixup_f32 v4, v4, v1, v16
	s_or_b64 exec, exec, s[0:1]
	s_and_saveexec_b64 s[0:1], s[22:23]
	v_readlane_b32 s79, v252, 40
	s_mov_b32 s33, 0x58000
	s_movk_i32 s40, 0x5800
	s_mov_b32 s41, 0x16000
	s_mov_b32 s42, 0x2c000
	s_mov_b32 s43, 0x42000
	s_mov_b32 s46, 0x6e000
	s_mov_b32 s47, 0x84000
	s_mov_b32 s50, 0x9a000
	s_mov_b32 s51, 0xb0000
	s_mov_b32 s52, 0xc6000
	s_mov_b32 s53, 0xdc000
	s_mov_b32 s56, 0xf2000
	s_mov_b32 s57, 0x108000
	v_readlane_b32 s90, v252, 43
	v_readlane_b32 s81, v252, 39
	s_cbranch_execz .LBB0_2145
; __device__ __forceinline__ unsigned pk2(float lo, float hi) { const bfx2 b = __builtin_convertvector((f32x2){lo, hi}, bfx2); return __builtin_bit_cast(unsigned, b); }
; __device__ __forceinline__ float bflo(unsigned w) { return __uint_as_float(w << 16); }
; __device__ __forceinline__ float bfhi(unsigned w) { return __uint_as_float(w & 0xffff0000u); }
; __device__ __forceinline__ void attn_item(const P& p, Frame& F, const bool is_s, const int b, const int g, const int c) {
;     ...
;               for (int hf = 0; hf < 2; ++hf) { const u32x4 o4 = *(const u32x4*)(PK + (2 * dt + hf) * 1024);
; #pragma unroll
;                   for (int rr = 0; rr < 2; ++rr) { const int r4 = 2 * hf + rr; const int d0 = 32 * dt + 8 * r4 + 4 * half; const u32x2 o = rr ? (u32x2){o4.z, o4.w} : (u32x2){o4.x, o4.y};
;                       u32x2 w; w.x = pk2(bflo(o.x) + ot[dt][4 * r4 + 0] * sc, bfhi(o.x) + ot[dt][4 * r4 + 1] * sc); w.y = pk2(bflo(o.y) + ot[dt][4 * r4 + 2] * sc, bfhi(o.y) + ot[dt][4 * r4 + 3] * sc);
;                       *(u32x2*)(YN + (size_t)mrow * 1024 + h * 128 + d0) = w; } } } }
	s_waitcnt vmcnt(0)
	v_lshlrev_b32_e32 v12, 16, v114
	v_and_b32_e32 v13, 0xffff0000, v114
	v_pk_fma_f32 v[12:13], v[66:67], v[4:5], v[12:13] op_sel_hi:[1,0,1]
	s_nop 0
	v_cvt_pk_bf16_f32 v114, v12, v13
	v_lshlrev_b32_e32 v14, 16, v115
	v_and_b32_e32 v15, 0xffff0000, v115
	v_pk_fma_f32 v[14:15], v[68:69], v[4:5], v[14:15] op_sel_hi:[1,0,1]
	s_nop 0
	v_cvt_pk_bf16_f32 v115, v14, v15
	global_store_dwordx2 v[6:7], v[114:115], off
	v_lshlrev_b32_e32 v16, 16, v116
	v_and_b32_e32 v17, 0xffff0000, v116
	v_pk_fma_f32 v[16:17], v[70:71], v[4:5], v[16:17] op_sel_hi:[1,0,1]
	s_nop 0
	v_cvt_pk_bf16_f32 v116, v16, v17
	v_lshlrev_b32_e32 v12, 16, v117
	v_and_b32_e32 v13, 0xffff0000, v117
	v_pk_fma_f32 v[12:13], v[72:73], v[4:5], v[12:13] op_sel_hi:[1,0,1]
	s_nop 0
	v_cvt_pk_bf16_f32 v117, v12, v13
	global_store_dwordx2 v[6:7], v[116:117], off offset:16
	v_lshlrev_b32_e32 v14, 16, v118
	v_and_b32_e32 v15, 0xffff0000, v118
	v_pk_fma_f32 v[14:15], v[74:75], v[4:5], v[14:15] op_sel_hi:[1,0,1]
	s_nop 0
	v_cvt_pk_bf16_f32 v118, v14, v15
	v_lshlrev_b32_e32 v16, 16, v119
	v_and_b32_e32 v17, 0xffff0000, v119
	v_pk_fma_f32 v[16:17], v[76:77], v[4:5], v[16:17] op_sel_hi:[1,0,1]
	s_nop 0
	v_cvt_pk_bf16_f32 v119, v16, v17
	global_store_dwordx2 v[6:7], v[118:119], off offset:32
	v_lshlrev_b32_e32 v12, 16, v120
	v_and_b32_e32 v13, 0xffff0000, v120
	v_pk_fma_f32 v[12:13], v[78:79], v[4:5], v[12:13] op_sel_hi:[1,0,1]
	s_nop 0
	v_cvt_pk_bf16_f32 v120, v12, v13
	v_lshlrev_b32_e32 v14, 16, v121
	v_and_b32_e32 v15, 0xffff0000, v121
	v_pk_fma_f32 v[14:15], v[80:81], v[4:5], v[14:15] op_sel_hi:[1,0,1]
	s_nop 0
	v_cvt_pk_bf16_f32 v121, v14, v15
	global_store_dwordx2 v[6:7], v[120:121], off offset:48
	v_lshlrev_b32_e32 v16, 16, v122
	v_and_b32_e32 v17, 0xffff0000, v122
	v_pk_fma_f32 v[16:17], v[50:51], v[4:5], v[16:17] op_sel_hi:[1,0,1]
	s_nop 0
	v_cvt_pk_bf16_f32 v122, v16, v17
	v_lshlrev_b32_e32 v12, 16, v123
	v_and_b32_e32 v13, 0xffff0000, v123
	v_pk_fma_f32 v[12:13], v[52:53], v[4:5], v[12:13] op_sel_hi:[1,0,1]
	s_nop 0
	v_cvt_pk_bf16_f32 v123, v12, v13
	global_store_dwordx2 v[6:7], v[122:123], off offset:64
	v_lshlrev_b32_e32 v14, 16, v124
	v_and_b32_e32 v15, 0xffff0000, v124
	v_pk_fma_f32 v[14:15], v[54:55], v[4:5], v[14:15] op_sel_hi:[1,0,1]
	s_nop 0
	v_cvt_pk_bf16_f32 v124, v14, v15
	v_lshlrev_b32_e32 v16, 16, v125
	v_and_b32_e32 v17, 0xffff0000, v125
	v_pk_fma_f32 v[16:17], v[56:57], v[4:5], v[16:17] op_sel_hi:[1,0,1]
	s_nop 0
	v_cvt_pk_bf16_f32 v125, v16, v17
	global_store_dwordx2 v[6:7], v[124:125], off offset:80
	v_lshlrev_b32_e32 v12, 16, v126
	v_and_b32_e32 v13, 0xffff0000, v126
	v_pk_fma_f32 v[12:13], v[58:59], v[4:5], v[12:13] op_sel_hi:[1,0,1]
	s_nop 0
	v_cvt_pk_bf16_f32 v126, v12, v13
	v_lshlrev_b32_e32 v14, 16, v127
	v_and_b32_e32 v15, 0xffff0000, v127
	v_pk_fma_f32 v[14:15], v[60:61], v[4:5], v[14:15] op_sel_hi:[1,0,1]
	s_nop 0
	v_cvt_pk_bf16_f32 v127, v14, v15
	global_store_dwordx2 v[6:7], v[126:127], off offset:96
	v_lshlrev_b32_e32 v16, 16, v128
	v_and_b32_e32 v17, 0xffff0000, v128
	v_pk_fma_f32 v[16:17], v[62:63], v[4:5], v[16:17] op_sel_hi:[1,0,1]
	s_nop 0
	v_cvt_pk_bf16_f32 v128, v16, v17
	v_lshlrev_b32_e32 v12, 16, v129
	v_and_b32_e32 v13, 0xffff0000, v129
	v_pk_fma_f32 v[12:13], v[64:65], v[4:5], v[12:13] op_sel_hi:[1,0,1]
	s_nop 0
	v_cvt_pk_bf16_f32 v129, v12, v13
	global_store_dwordx2 v[6:7], v[128:129], off offset:112
	v_lshlrev_b32_e32 v14, 16, v130
	v_and_b32_e32 v15, 0xffff0000, v130
	v_pk_fma_f32 v[14:15], v[34:35], v[4:5], v[14:15] op_sel_hi:[1,0,1]
	s_nop 0
	v_cvt_pk_bf16_f32 v130, v14, v15
	v_lshlrev_b32_e32 v16, 16, v131
	v_and_b32_e32 v17, 0xffff0000, v131
	v_pk_fma_f32 v[16:17], v[36:37], v[4:5], v[16:17] op_sel_hi:[1,0,1]
	s_nop 0
	v_cvt_pk_bf16_f32 v131, v16, v17
	global_store_dwordx2 v[6:7], v[130:131], off offset:128
	v_lshlrev_b32_e32 v12, 16, v132
	v_and_b32_e32 v13, 0xffff0000, v132
	v_pk_fma_f32 v[12:13], v[38:39], v[4:5], v[12:13] op_sel_hi:[1,0,1]
	s_nop 0
	v_cvt_pk_bf16_f32 v132, v12, v13
	v_lshlrev_b32_e32 v14, 16, v133
	v_and_b32_e32 v15, 0xffff0000, v133
	v_pk_fma_f32 v[14:15], v[40:41], v[4:5], v[14:15] op_sel_hi:[1,0,1]
	s_nop 0
	v_cvt_pk_bf16_f32 v133, v14, v15
	global_store_dwordx2 v[6:7], v[132:133], off offset:144
	v_lshlrev_b32_e32 v16, 16, v134
	v_and_b32_e32 v17, 0xffff0000, v134
	v_pk_fma_f32 v[16:17], v[42:43], v[4:5], v[16:17] op_sel_hi:[1,0,1]
	s_nop 0
	v_cvt_pk_bf16_f32 v134, v16, v17
	v_lshlrev_b32_e32 v12, 16, v135
	v_and_b32_e32 v13, 0xffff0000, v135
	v_pk_fma_f32 v[12:13], v[44:45], v[4:5], v[12:13] op_sel_hi:[1,0,1]
	s_nop 0
	v_cvt_pk_bf16_f32 v135, v12, v13
	global_store_dwordx2 v[6:7], v[134:135], off offset:160
	v_lshlrev_b32_e32 v14, 16, v136
	v_and_b32_e32 v15, 0xffff0000, v136
	v_pk_fma_f32 v[14:15], v[46:47], v[4:5], v[14:15] op_sel_hi:[1,0,1]
	s_nop 0
	v_cvt_pk_bf16_f32 v136, v14, v15
	v_lshlrev_b32_e32 v16, 16, v137
	v_and_b32_e32 v17, 0xffff0000, v137
	v_pk_fma_f32 v[16:17], v[48:49], v[4:5], v[16:17] op_sel_hi:[1,0,1]
	s_nop 0
	v_cvt_pk_bf16_f32 v137, v16, v17
	global_store_dwordx2 v[6:7], v[136:137], off offset:176
	v_lshlrev_b32_e32 v12, 16, v138
	v_and_b32_e32 v13, 0xffff0000, v138
	v_pk_fma_f32 v[12:13], v[18:19], v[4:5], v[12:13] op_sel_hi:[1,0,1]
	s_nop 0
	v_cvt_pk_bf16_f32 v138, v12, v13
	v_lshlrev_b32_e32 v14, 16, v139
	v_and_b32_e32 v15, 0xffff0000, v139
	v_pk_fma_f32 v[14:15], v[20:21], v[4:5], v[14:15] op_sel_hi:[1,0,1]
	s_nop 0
	v_cvt_pk_bf16_f32 v139, v14, v15
	global_store_dwordx2 v[6:7], v[138:139], off offset:192
	v_lshlrev_b32_e32 v16, 16, v140
	v_and_b32_e32 v17, 0xffff0000, v140
	v_pk_fma_f32 v[16:17], v[22:23], v[4:5], v[16:17] op_sel_hi:[1,0,1]
	s_nop 0
	v_cvt_pk_bf16_f32 v140, v16, v17
	v_lshlrev_b32_e32 v12, 16, v141
	v_and_b32_e32 v13, 0xffff0000, v141
	v_pk_fma_f32 v[12:13], v[24:25], v[4:5], v[12:13] op_sel_hi:[1,0,1]
	s_nop 0
	v_cvt_pk_bf16_f32 v141, v12, v13
	global_store_dwordx2 v[6:7], v[140:141], off offset:208
	v_lshlrev_b32_e32 v14, 16, v142
	v_and_b32_e32 v15, 0xffff0000, v142
	v_pk_fma_f32 v[14:15], v[26:27], v[4:5], v[14:15] op_sel_hi:[1,0,1]
	s_nop 0
	v_cvt_pk_bf16_f32 v142, v14, v15
	v_lshlrev_b32_e32 v16, 16, v143
	v_and_b32_e32 v17, 0xffff0000, v143
	v_pk_fma_f32 v[16:17], v[28:29], v[4:5], v[16:17] op_sel_hi:[1,0,1]
	s_nop 0
	v_cvt_pk_bf16_f32 v143, v16, v17
	global_store_dwordx2 v[6:7], v[142:143], off offset:224
	v_lshlrev_b32_e32 v12, 16, v144
	v_and_b32_e32 v13, 0xffff0000, v144
	v_pk_fma_f32 v[12:13], v[30:31], v[4:5], v[12:13] op_sel_hi:[1,0,1]
	s_nop 0
	v_cvt_pk_bf16_f32 v144, v12, v13
	v_lshlrev_b32_e32 v14, 16, v145
	v_and_b32_e32 v15, 0xffff0000, v145
	v_pk_fma_f32 v[14:15], v[32:33], v[4:5], v[14:15] op_sel_hi:[1,0,1]
	s_nop 0
	v_cvt_pk_bf16_f32 v145, v14, v15
	global_store_dwordx2 v[6:7], v[144:145], off offset:240
